# static priority raise (s_setprio 2) for the wave group running the bandwidth-bound merge epilogue
# baseline (speedup 1.0000x reference)
.Lmls_2:
	v_cvt_pk_bf16_f32 v36, v42, v36
	v_lshlrev_b32_e32 v37, 16, v105
	v_lshlrev_b32_e32 v42, 16, v101
	v_fmac_f32_e32 v37, v38, v42
	v_and_b32_e32 v38, 0xffff0000, v105
	v_and_b32_e32 v42, 0xffff0000, v101
	v_fmac_f32_e32 v38, v39, v42
	v_cvt_pk_bf16_f32 v37, v37, v38
	v_lshlrev_b32_e32 v38, 16, v106
	v_lshlrev_b32_e32 v39, 16, v102
	v_fmac_f32_e32 v38, v28, v39
	v_and_b32_e32 v28, 0xffff0000, v106
	v_and_b32_e32 v39, 0xffff0000, v102
	v_fmac_f32_e32 v28, v29, v39
	v_cvt_pk_bf16_f32 v38, v38, v28
	v_lshlrev_b32_e32 v28, 16, v107
	v_lshlrev_b32_e32 v29, 16, v103
	v_fmac_f32_e32 v28, v30, v29
	v_and_b32_e32 v29, 0xffff0000, v107
	v_and_b32_e32 v30, 0xffff0000, v103
	v_fmac_f32_e32 v29, v31, v30
	v_cvt_pk_bf16_f32 v39, v28, v29
	v_lshlrev_b32_e32 v28, 16, v80
	v_lshlrev_b32_e32 v29, 16, v92
	v_fmac_f32_e32 v28, v32, v29
	v_and_b32_e32 v29, 0xffff0000, v80
	v_and_b32_e32 v30, 0xffff0000, v92
	v_fmac_f32_e32 v29, v33, v30
	global_store_dwordx4 v[40:41], v[36:39], off offset:256
	v_cvt_pk_bf16_f32 v28, v28, v29
	v_lshlrev_b32_e32 v29, 16, v81
	v_lshlrev_b32_e32 v30, 16, v93
	v_fmac_f32_e32 v29, v34, v30
	v_and_b32_e32 v30, 0xffff0000, v81
	v_and_b32_e32 v31, 0xffff0000, v93
	v_fmac_f32_e32 v30, v35, v31
	v_cvt_pk_bf16_f32 v29, v29, v30
	v_lshlrev_b32_e32 v30, 16, v82
	v_lshlrev_b32_e32 v31, 16, v94
	v_fmac_f32_e32 v30, v24, v31
	v_and_b32_e32 v24, 0xffff0000, v82
	v_and_b32_e32 v31, 0xffff0000, v94
	v_fmac_f32_e32 v24, v25, v31
	v_cvt_pk_bf16_f32 v30, v30, v24
	v_lshlrev_b32_e32 v24, 16, v83
	v_lshlrev_b32_e32 v25, 16, v95
	v_add_u32_e32 v36, 0xa0, v210
	v_fmac_f32_e32 v24, v26, v25
	v_and_b32_e32 v25, 0xffff0000, v83
	v_and_b32_e32 v26, 0xffff0000, v95
	v_fmac_f32_e32 v25, v27, v26
	v_ashrrev_i32_e32 v37, 31, v36
	v_cvt_pk_bf16_f32 v31, v24, v25
	v_lshlrev_b64 v[24:25], 11, v[36:37]
	v_lshlrev_b32_e32 v26, 16, v88
	v_lshlrev_b32_e32 v27, 16, v84
	v_lshl_add_u64 v[24:25], s[0:1], 0, v[24:25]
	v_fmac_f32_e32 v26, v20, v27
	v_and_b32_e32 v20, 0xffff0000, v88
	v_and_b32_e32 v27, 0xffff0000, v84
	v_lshl_add_u64 v[24:25], v[24:25], 0, v[124:125]
	v_fmac_f32_e32 v20, v21, v27
	global_store_dwordx4 v[24:25], v[28:31], off
	v_cvt_pk_bf16_f32 v20, v26, v20
	v_lshlrev_b32_e32 v21, 16, v89
	v_lshlrev_b32_e32 v26, 16, v85
	v_fmac_f32_e32 v21, v22, v26
	v_and_b32_e32 v22, 0xffff0000, v89
	v_and_b32_e32 v26, 0xffff0000, v85
	v_fmac_f32_e32 v22, v23, v26
	v_cvt_pk_bf16_f32 v21, v21, v22
	v_lshlrev_b32_e32 v22, 16, v90
	v_lshlrev_b32_e32 v23, 16, v86
	v_fmac_f32_e32 v22, v12, v23
	v_and_b32_e32 v12, 0xffff0000, v90
	v_and_b32_e32 v23, 0xffff0000, v86
	v_fmac_f32_e32 v12, v13, v23
	v_cvt_pk_bf16_f32 v22, v22, v12
	v_lshlrev_b32_e32 v12, 16, v91
	v_lshlrev_b32_e32 v13, 16, v87
	v_fmac_f32_e32 v12, v14, v13
	v_and_b32_e32 v13, 0xffff0000, v91
	v_and_b32_e32 v14, 0xffff0000, v87
	v_fmac_f32_e32 v13, v15, v14
	v_cvt_pk_bf16_f32 v23, v12, v13
	v_lshlrev_b32_e32 v12, 16, v64
	v_lshlrev_b32_e32 v13, 16, v76
	v_fmac_f32_e32 v12, v16, v13
	v_and_b32_e32 v13, 0xffff0000, v64
	v_and_b32_e32 v14, 0xffff0000, v76
	v_fmac_f32_e32 v13, v17, v14
	global_store_dwordx4 v[24:25], v[20:23], off offset:256
	v_cvt_pk_bf16_f32 v12, v12, v13
	v_lshlrev_b32_e32 v13, 16, v65
	v_lshlrev_b32_e32 v14, 16, v77
	v_fmac_f32_e32 v13, v18, v14
	v_and_b32_e32 v14, 0xffff0000, v65
	v_and_b32_e32 v15, 0xffff0000, v77
	v_fmac_f32_e32 v14, v19, v15
	v_cvt_pk_bf16_f32 v13, v13, v14
	v_lshlrev_b32_e32 v14, 16, v66
	v_lshlrev_b32_e32 v15, 16, v78
	v_fmac_f32_e32 v14, v8, v15
	v_and_b32_e32 v8, 0xffff0000, v66
	v_and_b32_e32 v15, 0xffff0000, v78
	v_fmac_f32_e32 v8, v9, v15
	v_cvt_pk_bf16_f32 v14, v14, v8
	v_lshlrev_b32_e32 v8, 16, v67
	v_lshlrev_b32_e32 v9, 16, v79
	v_add_u32_e32 v20, 0xb0, v210
	v_fmac_f32_e32 v8, v10, v9
	v_and_b32_e32 v9, 0xffff0000, v67
	v_and_b32_e32 v10, 0xffff0000, v79
	v_fmac_f32_e32 v9, v11, v10
	v_ashrrev_i32_e32 v21, 31, v20
	v_cvt_pk_bf16_f32 v15, v8, v9
	v_lshlrev_b64 v[8:9], 11, v[20:21]
	v_lshlrev_b32_e32 v10, 16, v72
	v_lshlrev_b32_e32 v11, 16, v68
	v_lshl_add_u64 v[8:9], s[0:1], 0, v[8:9]
	v_fmac_f32_e32 v10, v4, v11
	v_and_b32_e32 v4, 0xffff0000, v72
	v_and_b32_e32 v11, 0xffff0000, v68
	v_lshl_add_u64 v[8:9], v[8:9], 0, v[124:125]
	v_fmac_f32_e32 v4, v5, v11
	global_store_dwordx4 v[8:9], v[12:15], off
	v_cvt_pk_bf16_f32 v4, v10, v4
	v_lshlrev_b32_e32 v5, 16, v73
	v_lshlrev_b32_e32 v10, 16, v69
	v_fmac_f32_e32 v5, v6, v10
	v_and_b32_e32 v6, 0xffff0000, v73
	v_and_b32_e32 v10, 0xffff0000, v69
	v_fmac_f32_e32 v6, v7, v10
	v_cvt_pk_bf16_f32 v5, v5, v6
	v_lshlrev_b32_e32 v6, 16, v74
	v_lshlrev_b32_e32 v7, 16, v70
	v_fmac_f32_e32 v6, v0, v7
	v_and_b32_e32 v0, 0xffff0000, v74
	v_and_b32_e32 v7, 0xffff0000, v70
	v_fmac_f32_e32 v0, v1, v7
	v_cvt_pk_bf16_f32 v6, v6, v0
	v_lshlrev_b32_e32 v0, 16, v75
	v_lshlrev_b32_e32 v1, 16, v71
	v_fmac_f32_e32 v0, v2, v1
	v_and_b32_e32 v1, 0xffff0000, v75
	v_and_b32_e32 v2, 0xffff0000, v71
	s_and_b64 vcc, exec, s[6:7]
	s_mov_b32 s37, s30
	s_mov_b32 s38, s34
	s_mov_b32 s39, s35
	s_mov_b32 s40, s36
	s_mov_b64 s[14:15], s[12:13]
	s_mov_b64 s[8:9], s[10:11]
	v_fmac_f32_e32 v1, v3, v2
	v_cvt_pk_bf16_f32 v7, v0, v1
	global_store_dwordx4 v[8:9], v[4:7], off offset:256
	s_waitcnt lgkmcnt(0)
	s_setprio 0
	s_cbranch_vccnz .LBB0_704

.LBB0_670:
	s_add_i32 s44, s14, 2
	s_add_u32 s15, s8, 0xfffc0080
	s_addc_u32 s16, s9, -1
	s_add_i32 s45, 0, 0x10000
	v_add_u32_e32 v140, s45, v237
	ds_read_b128 v[128:131], v140
	ds_read_b128 v[132:135], v140 offset:1024
	ds_read_b128 v[136:139], v140 offset:2048
	ds_read_b128 v[140:143], v140 offset:3072
	s_cmp_eq_u32 s41, s14
	s_cselect_b32 s14, s12, s42
	s_cselect_b32 s17, s11, s16
	s_cselect_b32 s16, s10, s15
	s_cselect_b32 s15, s13, s43
	v_lshl_add_u64 v[176:177], s[8:9], 0, v[206:207]
	s_add_i32 m0, s24, 0xc000
	ds_read_b128 v[144:147], v242
	ds_read_b128 v[148:151], v242 offset:1024
	ds_read_b128 v[152:155], v242 offset:2048
	ds_read_b128 v[156:159], v242 offset:3072
	ds_read_b128 v[160:163], v242 offset:4096
	ds_read_b128 v[164:167], v242 offset:5120
	ds_read_b128 v[168:171], v242 offset:6144
	ds_read_b128 v[172:175], v242 offset:7168
	global_load_lds_dwordx4 v[176:177], off
	v_lshl_add_u64 v[176:177], s[8:9], 0, v[208:209]
	s_add_i32 m0, s24, 0xe000
	s_nop 0
	global_load_lds_dwordx4 v[176:177], off
	s_waitcnt lgkmcnt(8)
	s_barrier
	s_waitcnt lgkmcnt(0)
	s_setprio 1
	s_waitcnt lgkmcnt(0)
	v_mfma_f32_16x16x32_bf16 v[124:127], v[128:131], v[144:147], v[124:127]
	v_mfma_f32_16x16x32_bf16 v[120:123], v[136:139], v[144:147], v[120:123]
	v_mfma_f32_16x16x32_bf16 v[112:115], v[128:131], v[152:155], v[112:115]
	v_mfma_f32_16x16x32_bf16 v[104:107], v[136:139], v[152:155], v[104:107]
	v_mfma_f32_16x16x32_bf16 v[96:99], v[128:131], v[160:163], v[96:99]
	v_mfma_f32_16x16x32_bf16 v[88:91], v[136:139], v[160:163], v[88:91]
	v_mfma_f32_16x16x32_bf16 v[80:83], v[128:131], v[168:171], v[80:83]
	v_mfma_f32_16x16x32_bf16 v[72:75], v[136:139], v[168:171], v[72:75]
	v_mfma_f32_16x16x32_bf16 v[124:127], v[132:135], v[148:151], v[124:127]
	v_mfma_f32_16x16x32_bf16 v[120:123], v[140:143], v[148:151], v[120:123]
	v_mfma_f32_16x16x32_bf16 v[112:115], v[132:135], v[156:159], v[112:115]
	v_mfma_f32_16x16x32_bf16 v[104:107], v[140:143], v[156:159], v[104:107]
	v_mfma_f32_16x16x32_bf16 v[96:99], v[132:135], v[164:167], v[96:99]
	v_mfma_f32_16x16x32_bf16 v[88:91], v[140:143], v[164:167], v[88:91]
	v_mfma_f32_16x16x32_bf16 v[80:83], v[132:135], v[172:175], v[80:83]
	v_mfma_f32_16x16x32_bf16 v[72:75], v[140:143], v[172:175], v[72:75]
	s_setprio 0
	s_barrier
	s_add_i32 s48, 0, 0x14000
	s_add_i32 s45, s45, s23
	v_add_u32_e32 v188, s48, v237
	v_lshl_add_u64 v[192:193], s[14:15], 0, v[194:195]
	s_mov_b32 m0, s45
	ds_read_b128 v[176:179], v188
	ds_read_b128 v[180:183], v188 offset:1024
	ds_read_b128 v[184:187], v188 offset:2048
	ds_read_b128 v[188:191], v188 offset:3072
	global_load_lds_dwordx4 v[192:193], off
	v_lshl_add_u64 v[210:211], s[14:15], 0, v[204:205]
	s_add_i32 m0, s45, 0x2000
	s_nop 0
	global_load_lds_dwordx4 v[210:211], off
	s_barrier
	s_waitcnt lgkmcnt(0)
	s_setprio 1
	s_waitcnt lgkmcnt(0)
	v_mfma_f32_16x16x32_bf16 v[116:119], v[176:179], v[144:147], v[116:119]
	v_mfma_f32_16x16x32_bf16 v[108:111], v[184:187], v[144:147], v[108:111]
	v_mfma_f32_16x16x32_bf16 v[100:103], v[176:179], v[152:155], v[100:103]
	v_mfma_f32_16x16x32_bf16 v[92:95], v[184:187], v[152:155], v[92:95]
	v_mfma_f32_16x16x32_bf16 v[84:87], v[176:179], v[160:163], v[84:87]
	v_mfma_f32_16x16x32_bf16 v[76:79], v[184:187], v[160:163], v[76:79]
	v_mfma_f32_16x16x32_bf16 v[68:71], v[176:179], v[168:171], v[68:71]
	v_mfma_f32_16x16x32_bf16 v[64:67], v[184:187], v[168:171], v[64:67]
	v_mfma_f32_16x16x32_bf16 v[116:119], v[180:183], v[148:151], v[116:119]
	v_mfma_f32_16x16x32_bf16 v[108:111], v[188:191], v[148:151], v[108:111]
	v_mfma_f32_16x16x32_bf16 v[100:103], v[180:183], v[156:159], v[100:103]
	v_mfma_f32_16x16x32_bf16 v[92:95], v[188:191], v[156:159], v[92:95]
	v_mfma_f32_16x16x32_bf16 v[84:87], v[180:183], v[164:167], v[84:87]
	v_mfma_f32_16x16x32_bf16 v[76:79], v[188:191], v[164:167], v[76:79]
	v_mfma_f32_16x16x32_bf16 v[68:71], v[180:183], v[172:175], v[68:71]
	v_mfma_f32_16x16x32_bf16 v[64:67], v[188:191], v[172:175], v[64:67]
	s_setprio 0
	s_mov_b32 m0, s24
	v_lshl_add_u64 v[212:213], s[16:17], 0, v[194:195]
	s_barrier
	ds_read_b128 v[144:147], v242 offset:16384
	ds_read_b128 v[148:151], v242 offset:17408
	ds_read_b128 v[152:155], v242 offset:18432
	ds_read_b128 v[156:159], v242 offset:19456
	ds_read_b128 v[160:163], v242 offset:20480
	ds_read_b128 v[164:167], v242 offset:21504
	ds_read_b128 v[168:171], v242 offset:22528
	ds_read_b128 v[172:175], v242 offset:23552
	global_load_lds_dwordx4 v[212:213], off
	v_lshl_add_u64 v[214:215], s[16:17], 0, v[204:205]
	s_mov_b32 m0, s25
	s_nop 0
	global_load_lds_dwordx4 v[214:215], off
	s_barrier
	s_waitcnt lgkmcnt(0)
	s_setprio 1
	s_waitcnt lgkmcnt(0)
	v_mfma_f32_16x16x32_bf16 v[60:63], v[128:131], v[144:147], v[60:63]
	v_mfma_f32_16x16x32_bf16 v[56:59], v[136:139], v[144:147], v[56:59]
	v_mfma_f32_16x16x32_bf16 v[48:51], v[128:131], v[152:155], v[48:51]
	v_mfma_f32_16x16x32_bf16 v[40:43], v[136:139], v[152:155], v[40:43]
	v_mfma_f32_16x16x32_bf16 v[32:35], v[128:131], v[160:163], v[32:35]
	v_mfma_f32_16x16x32_bf16 v[24:27], v[136:139], v[160:163], v[24:27]
	v_mfma_f32_16x16x32_bf16 v[16:19], v[128:131], v[168:171], v[16:19]
	v_mfma_f32_16x16x32_bf16 v[8:11], v[136:139], v[168:171], v[8:11]
	v_mfma_f32_16x16x32_bf16 v[60:63], v[132:135], v[148:151], v[60:63]
	v_mfma_f32_16x16x32_bf16 v[56:59], v[140:143], v[148:151], v[56:59]
	v_mfma_f32_16x16x32_bf16 v[48:51], v[132:135], v[156:159], v[48:51]
	v_mfma_f32_16x16x32_bf16 v[40:43], v[140:143], v[156:159], v[40:43]
	v_mfma_f32_16x16x32_bf16 v[32:35], v[132:135], v[164:167], v[32:35]
	v_mfma_f32_16x16x32_bf16 v[24:27], v[140:143], v[164:167], v[24:27]
	v_mfma_f32_16x16x32_bf16 v[16:19], v[132:135], v[172:175], v[16:19]
	v_mfma_f32_16x16x32_bf16 v[8:11], v[140:143], v[172:175], v[8:11]
	s_setprio 0
	s_barrier
	s_add_u32 s46, s14, 0x40000
	s_addc_u32 s47, s15, 0
	s_add_i32 s45, s48, s23
	v_lshl_add_u64 v[128:129], s[46:47], 0, v[194:195]
	s_mov_b32 m0, s45
	s_nop 0
	global_load_lds_dwordx4 v[128:129], off
	v_lshl_add_u64 v[128:129], s[46:47], 0, v[204:205]
	s_add_i32 m0, s45, 0x2000
	s_nop 0
	global_load_lds_dwordx4 v[128:129], off
	s_waitcnt vmcnt(6)
	s_barrier
	s_setprio 1
	v_mfma_f32_16x16x32_bf16 v[52:55], v[176:179], v[144:147], v[52:55]
	v_mfma_f32_16x16x32_bf16 v[44:47], v[184:187], v[144:147], v[44:47]
	v_mfma_f32_16x16x32_bf16 v[36:39], v[176:179], v[152:155], v[36:39]
	v_mfma_f32_16x16x32_bf16 v[28:31], v[184:187], v[152:155], v[28:31]
	v_mfma_f32_16x16x32_bf16 v[20:23], v[176:179], v[160:163], v[20:23]
	v_mfma_f32_16x16x32_bf16 v[12:15], v[184:187], v[160:163], v[12:15]
	v_mfma_f32_16x16x32_bf16 v[4:7], v[176:179], v[168:171], v[4:7]
	v_mfma_f32_16x16x32_bf16 v[0:3], v[184:187], v[168:171], v[0:3]
	v_mfma_f32_16x16x32_bf16 v[52:55], v[180:183], v[148:151], v[52:55]
	v_mfma_f32_16x16x32_bf16 v[44:47], v[188:191], v[148:151], v[44:47]
	v_mfma_f32_16x16x32_bf16 v[36:39], v[180:183], v[156:159], v[36:39]
	v_mfma_f32_16x16x32_bf16 v[28:31], v[188:191], v[156:159], v[28:31]
	v_mfma_f32_16x16x32_bf16 v[20:23], v[180:183], v[164:167], v[20:23]
	v_mfma_f32_16x16x32_bf16 v[12:15], v[188:191], v[164:167], v[12:15]
	v_mfma_f32_16x16x32_bf16 v[4:7], v[180:183], v[172:175], v[4:7]
	v_mfma_f32_16x16x32_bf16 v[0:3], v[188:191], v[172:175], v[0:3]
	s_setprio 0
	s_add_i32 s45, 0, 0x18000
	v_add_u32_e32 v140, s45, v237
	s_barrier
	ds_read_b128 v[128:131], v140
	ds_read_b128 v[132:135], v140 offset:1024
	ds_read_b128 v[136:139], v140 offset:2048
	ds_read_b128 v[140:143], v140 offset:3072
	s_add_u32 s16, s16, 0x40000
	s_addc_u32 s17, s17, 0
	s_mov_b32 m0, s26
	v_lshl_add_u64 v[176:177], s[16:17], 0, v[194:195]
	ds_read_b128 v[144:147], v242 offset:32768
	ds_read_b128 v[148:151], v242 offset:33792
	ds_read_b128 v[152:155], v242 offset:34816
	ds_read_b128 v[156:159], v242 offset:35840
	ds_read_b128 v[160:163], v242 offset:36864
	ds_read_b128 v[164:167], v242 offset:37888
	ds_read_b128 v[168:171], v242 offset:38912
	ds_read_b128 v[172:175], v242 offset:39936
	global_load_lds_dwordx4 v[176:177], off
	v_lshl_add_u64 v[176:177], s[16:17], 0, v[204:205]
	s_mov_b32 m0, s27
	s_nop 0
	global_load_lds_dwordx4 v[176:177], off
	s_waitcnt lgkmcnt(8)
	s_barrier
	s_waitcnt lgkmcnt(0)
	s_setprio 1
	s_waitcnt lgkmcnt(0)
	v_mfma_f32_16x16x32_bf16 v[124:127], v[128:131], v[144:147], v[124:127]
	v_mfma_f32_16x16x32_bf16 v[120:123], v[136:139], v[144:147], v[120:123]
	v_mfma_f32_16x16x32_bf16 v[112:115], v[128:131], v[152:155], v[112:115]
	v_mfma_f32_16x16x32_bf16 v[104:107], v[136:139], v[152:155], v[104:107]
	v_mfma_f32_16x16x32_bf16 v[96:99], v[128:131], v[160:163], v[96:99]
	v_mfma_f32_16x16x32_bf16 v[88:91], v[136:139], v[160:163], v[88:91]
	v_mfma_f32_16x16x32_bf16 v[80:83], v[128:131], v[168:171], v[80:83]
	v_mfma_f32_16x16x32_bf16 v[72:75], v[136:139], v[168:171], v[72:75]
	v_mfma_f32_16x16x32_bf16 v[124:127], v[132:135], v[148:151], v[124:127]
	v_mfma_f32_16x16x32_bf16 v[120:123], v[140:143], v[148:151], v[120:123]
	v_mfma_f32_16x16x32_bf16 v[112:115], v[132:135], v[156:159], v[112:115]
	v_mfma_f32_16x16x32_bf16 v[104:107], v[140:143], v[156:159], v[104:107]
	v_mfma_f32_16x16x32_bf16 v[96:99], v[132:135], v[164:167], v[96:99]
	v_mfma_f32_16x16x32_bf16 v[88:91], v[140:143], v[164:167], v[88:91]
	v_mfma_f32_16x16x32_bf16 v[80:83], v[132:135], v[172:175], v[80:83]
	v_mfma_f32_16x16x32_bf16 v[72:75], v[140:143], v[172:175], v[72:75]
	s_setprio 0
	s_barrier
	s_add_i32 s16, 0, 0x1c000
	s_add_i32 s17, s45, s23
	v_add_u32_e32 v188, s16, v237
	v_lshl_add_u64 v[192:193], v[192:193], 0, s[82:83]
	s_mov_b32 m0, s17
	ds_read_b128 v[176:179], v188
	ds_read_b128 v[180:183], v188 offset:1024
	ds_read_b128 v[184:187], v188 offset:2048
	ds_read_b128 v[188:191], v188 offset:3072
	global_load_lds_dwordx4 v[192:193], off
	v_lshl_add_u64 v[192:193], v[210:211], 0, s[82:83]
	s_add_i32 m0, s17, 0x2000
	s_nop 0
	global_load_lds_dwordx4 v[192:193], off
	s_barrier
	s_waitcnt lgkmcnt(0)
	s_setprio 1
	s_waitcnt lgkmcnt(0)
	v_mfma_f32_16x16x32_bf16 v[116:119], v[176:179], v[144:147], v[116:119]
	v_mfma_f32_16x16x32_bf16 v[108:111], v[184:187], v[144:147], v[108:111]
	v_mfma_f32_16x16x32_bf16 v[100:103], v[176:179], v[152:155], v[100:103]
	v_mfma_f32_16x16x32_bf16 v[92:95], v[184:187], v[152:155], v[92:95]
	v_mfma_f32_16x16x32_bf16 v[84:87], v[176:179], v[160:163], v[84:87]
	v_mfma_f32_16x16x32_bf16 v[76:79], v[184:187], v[160:163], v[76:79]
	v_mfma_f32_16x16x32_bf16 v[68:71], v[176:179], v[168:171], v[68:71]
	v_mfma_f32_16x16x32_bf16 v[64:67], v[184:187], v[168:171], v[64:67]
	v_mfma_f32_16x16x32_bf16 v[116:119], v[180:183], v[148:151], v[116:119]
	v_mfma_f32_16x16x32_bf16 v[108:111], v[188:191], v[148:151], v[108:111]
	v_mfma_f32_16x16x32_bf16 v[100:103], v[180:183], v[156:159], v[100:103]
	v_mfma_f32_16x16x32_bf16 v[92:95], v[188:191], v[156:159], v[92:95]
	v_mfma_f32_16x16x32_bf16 v[84:87], v[180:183], v[164:167], v[84:87]
	v_mfma_f32_16x16x32_bf16 v[76:79], v[188:191], v[164:167], v[76:79]
	v_mfma_f32_16x16x32_bf16 v[68:71], v[180:183], v[172:175], v[68:71]
	v_mfma_f32_16x16x32_bf16 v[64:67], v[188:191], v[172:175], v[64:67]
	s_setprio 0
	s_mov_b32 m0, s28
	v_lshl_add_u64 v[192:193], v[212:213], 0, s[82:83]
	s_barrier
	ds_read_b128 v[144:147], v242 offset:49152
	ds_read_b128 v[148:151], v242 offset:50176
	ds_read_b128 v[152:155], v242 offset:51200
	ds_read_b128 v[156:159], v242 offset:52224
	ds_read_b128 v[160:163], v242 offset:53248
	ds_read_b128 v[164:167], v242 offset:54272
	ds_read_b128 v[168:171], v242 offset:55296
	ds_read_b128 v[172:175], v242 offset:56320
	global_load_lds_dwordx4 v[192:193], off
	v_lshl_add_u64 v[192:193], v[214:215], 0, s[82:83]
	s_mov_b32 m0, s29
	s_nop 0
	global_load_lds_dwordx4 v[192:193], off
	s_barrier
	s_waitcnt lgkmcnt(0)
	s_setprio 1
	s_waitcnt lgkmcnt(0)
	v_mfma_f32_16x16x32_bf16 v[60:63], v[128:131], v[144:147], v[60:63]
	v_mfma_f32_16x16x32_bf16 v[56:59], v[136:139], v[144:147], v[56:59]
	v_mfma_f32_16x16x32_bf16 v[48:51], v[128:131], v[152:155], v[48:51]
	v_mfma_f32_16x16x32_bf16 v[40:43], v[136:139], v[152:155], v[40:43]
	v_mfma_f32_16x16x32_bf16 v[32:35], v[128:131], v[160:163], v[32:35]
	v_mfma_f32_16x16x32_bf16 v[24:27], v[136:139], v[160:163], v[24:27]
	v_mfma_f32_16x16x32_bf16 v[16:19], v[128:131], v[168:171], v[16:19]
	v_mfma_f32_16x16x32_bf16 v[8:11], v[136:139], v[168:171], v[8:11]
	v_mfma_f32_16x16x32_bf16 v[60:63], v[132:135], v[148:151], v[60:63]
	v_mfma_f32_16x16x32_bf16 v[56:59], v[140:143], v[148:151], v[56:59]
	v_mfma_f32_16x16x32_bf16 v[48:51], v[132:135], v[156:159], v[48:51]
	v_mfma_f32_16x16x32_bf16 v[40:43], v[140:143], v[156:159], v[40:43]
	v_mfma_f32_16x16x32_bf16 v[32:35], v[132:135], v[164:167], v[32:35]
	v_mfma_f32_16x16x32_bf16 v[24:27], v[140:143], v[164:167], v[24:27]
	v_mfma_f32_16x16x32_bf16 v[16:19], v[132:135], v[172:175], v[16:19]
	v_mfma_f32_16x16x32_bf16 v[8:11], v[140:143], v[172:175], v[8:11]
	s_setprio 0
	s_barrier
	s_add_u32 s14, s14, 0x40080
	s_addc_u32 s15, s15, 0
	s_add_i32 s16, s16, s23
	v_lshl_add_u64 v[128:129], s[14:15], 0, v[194:195]
	s_mov_b32 m0, s16
	s_nop 0
	global_load_lds_dwordx4 v[128:129], off
	v_lshl_add_u64 v[128:129], s[14:15], 0, v[204:205]
	s_add_i32 m0, s16, 0x2000
	s_nop 0
	global_load_lds_dwordx4 v[128:129], off
	s_waitcnt vmcnt(6)
	s_barrier
	s_setprio 1
	v_mfma_f32_16x16x32_bf16 v[52:55], v[176:179], v[144:147], v[52:55]
	v_mfma_f32_16x16x32_bf16 v[44:47], v[184:187], v[144:147], v[44:47]
	v_mfma_f32_16x16x32_bf16 v[36:39], v[176:179], v[152:155], v[36:39]
	v_mfma_f32_16x16x32_bf16 v[28:31], v[184:187], v[152:155], v[28:31]
	v_mfma_f32_16x16x32_bf16 v[20:23], v[176:179], v[160:163], v[20:23]
	v_mfma_f32_16x16x32_bf16 v[12:15], v[184:187], v[160:163], v[12:15]
	v_mfma_f32_16x16x32_bf16 v[4:7], v[176:179], v[168:171], v[4:7]
	v_mfma_f32_16x16x32_bf16 v[0:3], v[184:187], v[168:171], v[0:3]
	v_mfma_f32_16x16x32_bf16 v[52:55], v[180:183], v[148:151], v[52:55]
	v_mfma_f32_16x16x32_bf16 v[44:47], v[188:191], v[148:151], v[44:47]
	v_mfma_f32_16x16x32_bf16 v[36:39], v[180:183], v[156:159], v[36:39]
	v_mfma_f32_16x16x32_bf16 v[28:31], v[188:191], v[156:159], v[28:31]
	v_mfma_f32_16x16x32_bf16 v[20:23], v[180:183], v[164:167], v[20:23]
	v_mfma_f32_16x16x32_bf16 v[12:15], v[188:191], v[164:167], v[12:15]
	v_mfma_f32_16x16x32_bf16 v[4:7], v[180:183], v[172:175], v[4:7]
	v_mfma_f32_16x16x32_bf16 v[0:3], v[188:191], v[172:175], v[0:3]
	s_setprio 0
	s_add_u32 s8, s8, 0x100
	s_addc_u32 s9, s9, 0
	s_add_u32 s42, s42, 0x100
	s_addc_u32 s43, s43, 0
	s_cmp_ge_i32 s44, s40
	s_mov_b32 s14, s44
	s_barrier
	s_cbranch_scc0 .LBB0_670
	s_setprio 2
	s_lshl_b32 s8, s37, 10
	s_ashr_i32 s9, s8, 31
	s_cmp_gt_i32 s37, 0
	s_cselect_b64 s[16:17], -1, 0
	s_lshl_b32 s39, s39, 8
	s_lshl_b64 s[8:9], s[8:9], 1
	s_add_u32 s14, s3, s8
	s_addc_u32 s15, s18, s9
	v_add_u32_e32 v210, s39, v236
	v_lshl_or_b32 v212, s38, 8, v241
	v_mov_b64_e32 v[128:129], s[14:15]
	v_mad_i64_i32 v[128:129], s[8:9], v210, s81, v[128:129]
	v_ashrrev_i32_e32 v213, 31, v212
	v_lshl_add_u64 v[130:131], v[212:213], 1, v[128:129]
	global_load_dwordx4 v[186:189], v[130:131], off
	v_ashrrev_i32_e32 v211, 31, v210
	v_lshlrev_b64 v[128:129], 11, v[210:211]
	v_lshl_add_u64 v[214:215], s[0:1], 0, v[128:129]
	s_cmp_lt_i32 s37, 1
	v_lshl_add_u64 v[128:129], v[212:213], 1, v[214:215]
	s_cbranch_scc1 .LBB0_673
	v_mov_b32_e32 v190, v243
	v_mov_b32_e32 v191, v244
	v_mov_b32_e32 v192, v245
	v_mov_b32_e32 v193, v246
	s_branch .LBB0_674
